# attention tile loops: next-tile global_load_lds issue moved from the segment head to after the current tile's LDS reads are issued
# baseline (speedup 1.0000x reference)
.Ld_np:
.LBB0_852:
	s_waitcnt vmcnt(0)
	s_and_b32 s7, s6, 1
	s_add_i32 s3, s6, 1
	s_barrier
	s_cmp_gt_i32 s6, s2
	s_cbranch_scc0 .LBB0_856
	s_cmp_ge_u32 s3, s71
	s_cbranch_scc1 .LBB0_854
	s_lshl_b32 s8, s7, 15
	s_xor_b32 s8, s8, 0x8000
	s_add_i32 s8, s8, 0
	v_add_u32_e32 v0, s50, v142
	v_lshlrev_b64 v[82:83], 11, v[0:1]
	s_add_i32 s9, s8, s72
	v_lshl_add_u64 v[82:83], s[88:89], 0, v[82:83]
	s_mov_b32 m0, s9
	v_add_u32_e32 v0, s50, v141
	global_load_lds_dwordx4 v[82:83], off
	v_lshl_add_u64 v[82:83], v[82:83], 0, s[54:55]
	s_add_i32 m0, s9, 0x2000
	s_add_i32 s8, s8, s76
	global_load_lds_dwordx4 v[82:83], off
	v_lshlrev_b64 v[82:83], 11, v[0:1]
	v_lshl_add_u64 v[82:83], s[74:75], 0, v[82:83]
	v_lshl_add_u64 v[84:85], s[84:85], 1, v[82:83]
	v_lshlrev_b32_e32 v0, 1, v132
	v_lshl_add_u64 v[84:85], v[84:85], 0, v[0:1]
	s_add_i32 m0, s9, 0x4000
	v_lshl_add_u64 v[82:83], s[86:87], 1, v[82:83]
	global_load_lds_dwordx4 v[84:85], off
	v_lshl_add_u64 v[82:83], v[82:83], 0, v[0:1]
	s_add_i32 m0, s8, 0x4000
	s_nop 0
	global_load_lds_dwordx4 v[82:83], off

.LBB0_856:
	s_lshl_b32 s6, s7, 15
	s_add_i32 s64, s6, 0
	s_add_i32 s6, s64, s92
	v_add3_u32 v253, s6, v136, v137
	v_add_u32_e32 v252, s64, v138
	ds_read_b128 v[186:189], v253
	ds_read_b128 v[190:193], v253 offset:512
	ds_read_b128 v[194:197], v253 offset:2048
	ds_read_b128 v[198:201], v253 offset:2560
	v_add3_u32 v252, v252, v132, v139
	ds_read_b128 v[202:205], v253 offset:4096
	ds_read_b128 v[206:209], v253 offset:4608
	ds_read_b128 v[210:213], v253 offset:6144
	ds_read_b128 v[214:217], v253 offset:6656
	ds_read_b64_tr_b16 v[236:237], v252 offset:16384
	ds_read_b64_tr_b16 v[238:239], v252 offset:16896
	ds_read_b64_tr_b16 v[240:241], v252 offset:17408
	ds_read_b64_tr_b16 v[242:243], v252 offset:17920
	ds_read_b64_tr_b16 v[244:245], v252 offset:18432
	ds_read_b64_tr_b16 v[246:247], v252 offset:18944
	ds_read_b64_tr_b16 v[248:249], v252 offset:19456
	s_cmp_ge_u32 s3, s71
	s_cbranch_scc1 .Ld_noissue
	s_lshl_b32 s8, s7, 15
	s_xor_b32 s8, s8, 0x8000
	s_add_i32 s8, s8, 0
	v_add_u32_e32 v0, s50, v142
	v_lshlrev_b64 v[82:83], 11, v[0:1]
	s_add_i32 s9, s8, s72
	v_lshl_add_u64 v[82:83], s[88:89], 0, v[82:83]
	s_mov_b32 m0, s9
	v_add_u32_e32 v0, s50, v141
	global_load_lds_dwordx4 v[82:83], off
	v_lshl_add_u64 v[82:83], v[82:83], 0, s[54:55]
	s_add_i32 m0, s9, 0x2000
	s_add_i32 s8, s8, s76
	global_load_lds_dwordx4 v[82:83], off
	v_lshlrev_b64 v[82:83], 11, v[0:1]
	v_lshl_add_u64 v[82:83], s[74:75], 0, v[82:83]
	v_lshl_add_u64 v[84:85], s[84:85], 1, v[82:83]
	v_lshlrev_b32_e32 v0, 1, v132
	v_lshl_add_u64 v[84:85], v[84:85], 0, v[0:1]
	s_add_i32 m0, s9, 0x4000
	v_lshl_add_u64 v[82:83], s[86:87], 1, v[82:83]
	global_load_lds_dwordx4 v[84:85], off
	v_lshl_add_u64 v[82:83], v[82:83], 0, v[0:1]
	s_add_i32 m0, s8, 0x4000
	s_nop 0
	global_load_lds_dwordx4 v[82:83], off
.Ld_noissue:
	s_waitcnt lgkmcnt(14)
	v_mfma_f32_32x32x16_bf16 v[82:97], v[186:189], v[114:117], v[66:81]
	s_waitcnt lgkmcnt(13)
	v_mfma_f32_32x32x16_bf16 v[98:113], v[190:193], v[114:117], v[66:81]
	ds_read_b64_tr_b16 v[250:251], v252 offset:19968
	s_waitcnt lgkmcnt(13)
	v_mfma_f32_32x32x16_bf16 v[82:97], v[194:197], v[118:121], v[82:97]
	s_waitcnt lgkmcnt(12)
	v_mfma_f32_32x32x16_bf16 v[98:113], v[198:201], v[118:121], v[98:113]
	s_waitcnt lgkmcnt(11)
	v_mfma_f32_32x32x16_bf16 v[82:97], v[202:205], v[122:125], v[82:97]
	s_waitcnt lgkmcnt(10)
	v_mfma_f32_32x32x16_bf16 v[98:113], v[206:209], v[122:125], v[98:113]
	s_waitcnt lgkmcnt(9)
	v_mfma_f32_32x32x16_bf16 v[82:97], v[210:213], v[126:129], v[82:97]
	s_waitcnt lgkmcnt(8)
	v_mfma_f32_32x32x16_bf16 v[98:113], v[214:217], v[126:129], v[98:113]
	ds_read_b64_tr_b16 v[186:187], v252 offset:20480
	ds_read_b64_tr_b16 v[188:189], v252 offset:20992
	ds_read_b64_tr_b16 v[190:191], v252 offset:21504
	ds_read_b64_tr_b16 v[192:193], v252 offset:22016
	ds_read_b64_tr_b16 v[194:195], v252 offset:22528
	ds_read_b64_tr_b16 v[196:197], v252 offset:23040
	ds_read_b64_tr_b16 v[198:199], v252 offset:23552
	ds_read_b64_tr_b16 v[200:201], v252 offset:24064
	ds_read_b64_tr_b16 v[202:203], v252 offset:24576
	ds_read_b64_tr_b16 v[204:205], v252 offset:25088
	ds_read_b64_tr_b16 v[206:207], v252 offset:25600
	ds_read_b64_tr_b16 v[208:209], v252 offset:26112
	ds_read_b64_tr_b16 v[210:211], v252 offset:26624
	ds_read_b64_tr_b16 v[212:213], v252 offset:27136
	ds_read_b64_tr_b16 v[214:215], v252 offset:27648
	ds_read_b64_tr_b16 v[216:217], v252 offset:28160
	v_add_u32_e32 v0, 59, v140
	s_add_i32 s6, s50, 0xb0
	s_cmp_le_i32 s6, s53
	s_cbranch_scc1 .LBB0_858
	v_add_u32_e32 v144, 58, v140
	v_med3_i32 v144, v144, 0, v234
	v_lshl_add_u32 v145, v144, 2, s73
	v_add_u32_e32 v144, 57, v140
	v_med3_i32 v144, v144, 0, v234
	v_add_u32_e32 v152, 42, v140
	v_lshl_add_u32 v146, v144, 2, s73
	v_add_u32_e32 v144, 56, v140
	v_med3_i32 v152, v152, 0, v234
	v_med3_i32 v144, v144, 0, v234
	v_lshl_add_u32 v153, v152, 2, s73
	v_add_u32_e32 v152, 41, v140
	v_lshl_add_u32 v147, v144, 2, s73
	v_add_u32_e32 v144, 51, v140
	v_med3_i32 v152, v152, 0, v234
	v_add_u32_e32 v160, 26, v140
	v_med3_i32 v144, v144, 0, v234
	v_lshl_add_u32 v154, v152, 2, s73
	v_add_u32_e32 v152, 40, v140
	v_med3_i32 v160, v160, 0, v234
	v_lshl_add_u32 v148, v144, 2, s73
	v_add_u32_e32 v144, 50, v140
	v_med3_i32 v152, v152, 0, v234
	v_lshl_add_u32 v161, v160, 2, s73
	v_add_u32_e32 v160, 25, v140
	v_med3_i32 v144, v144, 0, v234
	v_lshl_add_u32 v155, v152, 2, s73
	v_add_u32_e32 v152, 35, v140
	v_med3_i32 v160, v160, 0, v234
	v_lshl_add_u32 v149, v144, 2, s73
	v_add_u32_e32 v144, 49, v140
	v_med3_i32 v152, v152, 0, v234
	v_lshl_add_u32 v162, v160, 2, s73
	v_add_u32_e32 v160, 24, v140
	v_add_u32_e32 v168, 10, v140
	v_med3_i32 v144, v144, 0, v234
	v_lshl_add_u32 v156, v152, 2, s73
	v_add_u32_e32 v152, 34, v140
	v_med3_i32 v160, v160, 0, v234
	v_med3_i32 v168, v168, 0, v234
	v_lshl_add_u32 v150, v144, 2, s73
	v_add_u32_e32 v144, 48, v140
	v_med3_i32 v152, v152, 0, v234
	v_lshl_add_u32 v163, v160, 2, s73
	v_add_u32_e32 v160, 19, v140
	v_lshl_add_u32 v169, v168, 2, s73
	v_add_u32_e32 v168, 9, v140
	v_med3_i32 v143, v0, 0, v234
	v_med3_i32 v144, v144, 0, v234
	v_lshl_add_u32 v157, v152, 2, s73
	v_add_u32_e32 v152, 33, v140
	v_med3_i32 v160, v160, 0, v234
	v_med3_i32 v168, v168, 0, v234
	v_lshl_add_u32 v143, v143, 2, s73
	v_lshl_add_u32 v151, v144, 2, s73
	v_med3_i32 v152, v152, 0, v234
	v_lshl_add_u32 v164, v160, 2, s73
	v_add_u32_e32 v160, 18, v140
	v_lshl_add_u32 v180, v168, 2, s73
	v_add_u32_e32 v168, 8, v140
	ds_read_b32 v144, v143
	ds_read_b32 v145, v145
	ds_read_b32 v146, v146
	ds_read_b32 v147, v147
	ds_read_b32 v148, v148
	ds_read_b32 v149, v149
	ds_read_b32 v150, v150
	ds_read_b32 v151, v151
	v_add_u32_e32 v143, 43, v140
	v_lshl_add_u32 v158, v152, 2, s73
	v_add_u32_e32 v152, 32, v140
	v_med3_i32 v160, v160, 0, v234
	v_med3_i32 v168, v168, 0, v234
	v_med3_i32 v143, v143, 0, v234
	v_med3_i32 v152, v152, 0, v234
	v_lshl_add_u32 v165, v160, 2, s73
	v_add_u32_e32 v160, 17, v140
	v_lshl_add_u32 v181, v168, 2, s73
	v_add_u32_e32 v168, 3, v140
	v_lshl_add_u32 v143, v143, 2, s73
	v_lshl_add_u32 v159, v152, 2, s73
	v_med3_i32 v160, v160, 0, v234
	v_med3_i32 v168, v168, 0, v234
	ds_read_b32 v152, v143
	ds_read_b32 v153, v153
	ds_read_b32 v154, v154
	ds_read_b32 v155, v155
	ds_read_b32 v156, v156
	ds_read_b32 v157, v157
	ds_read_b32 v158, v158
	ds_read_b32 v159, v159
	v_add_u32_e32 v143, 27, v140
	v_lshl_add_u32 v166, v160, 2, s73
	v_add_u32_e32 v160, 16, v140
	v_lshl_add_u32 v182, v168, 2, s73
	v_add_u32_e32 v168, 2, v140
	v_med3_i32 v143, v143, 0, v234
	v_med3_i32 v160, v160, 0, v234
	v_med3_i32 v168, v168, 0, v234
	v_lshl_add_u32 v143, v143, 2, s73
	v_lshl_add_u32 v167, v160, 2, s73
	v_lshl_add_u32 v183, v168, 2, s73
	v_add_u32_e32 v168, 1, v140
	ds_read_b32 v160, v143
	ds_read_b32 v161, v161
	ds_read_b32 v162, v162
	ds_read_b32 v163, v163
	ds_read_b32 v164, v164
	ds_read_b32 v165, v165
	ds_read_b32 v166, v166
	ds_read_b32 v167, v167
	v_add_u32_e32 v143, 11, v140
	v_med3_i32 v168, v168, 0, v234
	v_med3_i32 v143, v143, 0, v234
	v_lshl_add_u32 v184, v168, 2, s73
	v_med3_i32 v168, v140, 0, v234
	v_lshl_add_u32 v143, v143, 2, s73
	v_lshl_add_u32 v185, v168, 2, s73
	ds_read_b32 v168, v143
	ds_read_b32 v169, v169
	ds_read_b32 v180, v180
	ds_read_b32 v181, v181
	ds_read_b32 v182, v182
	ds_read_b32 v183, v183
	ds_read_b32 v184, v184
	ds_read_b32 v185, v185
	s_waitcnt lgkmcnt(0)
	v_pk_add_f32 v[96:97], v[96:97], v[158:159]
	v_pk_add_f32 v[94:95], v[94:95], v[156:157]
	v_pk_add_f32 v[92:93], v[92:93], v[154:155]
	v_pk_add_f32 v[90:91], v[90:91], v[152:153]
	v_pk_add_f32 v[88:89], v[88:89], v[150:151]
	v_pk_add_f32 v[86:87], v[86:87], v[148:149]
	v_pk_add_f32 v[84:85], v[84:85], v[146:147]
	v_pk_add_f32 v[82:83], v[82:83], v[144:145]
	v_pk_add_f32 v[112:113], v[112:113], v[184:185]
	v_pk_add_f32 v[110:111], v[110:111], v[182:183]
	v_pk_add_f32 v[108:109], v[108:109], v[180:181]
	v_pk_add_f32 v[106:107], v[106:107], v[168:169]
	v_pk_add_f32 v[104:105], v[104:105], v[166:167]
	v_pk_add_f32 v[102:103], v[102:103], v[164:165]
	v_pk_add_f32 v[100:101], v[100:101], v[162:163]
	v_pk_add_f32 v[98:99], v[98:99], v[160:161]

.Lf_np:
.LBB0_875:
	s_and_b32 s72, s6, 1
	s_add_i32 s71, s6, 1
	s_waitcnt vmcnt(0)
	s_cmp_ge_u32 s71, s41
	s_cselect_b64 s[78:79], -1, 0
	s_waitcnt lgkmcnt(0)
	s_barrier
	s_cmp_gt_i32 s6, s53
	s_cbranch_scc0 .Lf_compute
	s_and_b64 vcc, exec, s[78:79]
	s_cbranch_vccnz .LBB0_883
	s_lshl_b32 s7, s72, 15
	s_add_i32 s50, s60, 1
	s_xor_b32 s7, s7, 0x8000
	v_add_u32_e32 v0, s50, v128
	v_lshlrev_b64 v[2:3], 11, v[0:1]
	s_add_i32 s7, s2, s7
	v_lshl_add_u64 v[2:3], s[88:89], 0, v[2:3]
	s_mov_b32 m0, s7
	v_add_u32_e32 v0, s50, v138
	global_load_lds_dwordx4 v[2:3], off
	v_lshlrev_b64 v[2:3], 11, v[0:1]
	v_lshl_add_u64 v[2:3], v[132:133], 0, v[2:3]
	s_add_i32 m0, s7, 0x4000
	s_andn2_b64 vcc, exec, s[86:87]
	global_load_lds_dwordx4 v[2:3], off
	s_cbranch_vccnz .LBB0_883
	v_lshl_add_u64 v[2:3], s[50:51], 2, v[130:131]
	global_load_dword v145, v[2:3], off
	s_branch .LBB0_883
.Lf_compute:
	v_lshl_add_u32 v252, s72, 8, v139
	s_lshl_b32 s6, s72, 15
	s_add_i32 s45, s6, 0
	ds_read_b128 v[80:83], v252
	ds_read_b128 v[84:87], v252 offset:32
	ds_read_b128 v[88:91], v252 offset:64
	ds_read_b128 v[92:95], v252 offset:96
	v_add3_u32 v253, s45, v140, v141
	ds_read_b128 v[96:99], v252 offset:128
	ds_read_b128 v[100:103], v252 offset:160
	ds_read_b128 v[104:107], v252 offset:192
	ds_read_b128 v[108:111], v252 offset:224
	v_add_u32_e32 v250, s45, v142
	ds_read_b128 v[146:149], v253
	ds_read_b128 v[150:153], v253 offset:512
	ds_read_b128 v[154:157], v253 offset:2048
	ds_read_b128 v[158:161], v253 offset:2560
	v_add3_u32 v250, v250, v129, v143
	ds_read_b128 v[162:165], v253 offset:4096
	ds_read_b128 v[166:169], v253 offset:4608
	ds_read_b128 v[180:183], v253 offset:6144
	ds_read_b128 v[184:187], v253 offset:6656
	s_and_b64 vcc, exec, s[78:79]
	s_cbranch_vccnz .Lf_noissue
	s_lshl_b32 s7, s72, 15
	s_add_i32 s50, s60, 1
	s_xor_b32 s7, s7, 0x8000
	v_add_u32_e32 v0, s50, v128
	v_lshlrev_b64 v[2:3], 11, v[0:1]
	s_add_i32 s7, s2, s7
	v_lshl_add_u64 v[2:3], s[88:89], 0, v[2:3]
	s_mov_b32 m0, s7
	v_add_u32_e32 v0, s50, v138
	global_load_lds_dwordx4 v[2:3], off
	v_lshlrev_b64 v[2:3], 11, v[0:1]
	v_lshl_add_u64 v[2:3], v[132:133], 0, v[2:3]
	s_add_i32 m0, s7, 0x4000
	s_andn2_b64 vcc, exec, s[86:87]
	global_load_lds_dwordx4 v[2:3], off
	s_cbranch_vccnz .Lf_noissue
	v_lshl_add_u64 v[2:3], s[50:51], 2, v[130:131]
	global_load_dword v145, v[2:3], off
.Lf_noissue:
	s_waitcnt lgkmcnt(8)
	v_sub_f32_e32 v80, v48, v80
	v_sub_f32_e32 v81, v48, v81
	v_sub_f32_e32 v82, v48, v82
	v_sub_f32_e32 v83, v48, v83
	v_sub_f32_e32 v84, v48, v84
	v_sub_f32_e32 v85, v48, v85
	v_sub_f32_e32 v86, v48, v86
	v_sub_f32_e32 v87, v48, v87
	v_sub_f32_e32 v88, v48, v88
	v_sub_f32_e32 v89, v48, v89
	v_sub_f32_e32 v90, v48, v90
	v_sub_f32_e32 v91, v48, v91
	v_sub_f32_e32 v92, v48, v92
	v_sub_f32_e32 v93, v48, v93
	v_sub_f32_e32 v94, v48, v94
	v_sub_f32_e32 v95, v48, v95
	ds_read_b64_tr_b16 v[188:189], v250 offset:16384
	ds_read_b64_tr_b16 v[190:191], v250 offset:16896
	ds_read_b64_tr_b16 v[192:193], v250 offset:17408
	ds_read_b64_tr_b16 v[194:195], v250 offset:17920
	v_sub_f32_e32 v96, v48, v96
	v_sub_f32_e32 v97, v48, v97
	v_sub_f32_e32 v98, v48, v98
	v_sub_f32_e32 v99, v48, v99
	v_sub_f32_e32 v100, v48, v100
	v_sub_f32_e32 v101, v48, v101
	v_sub_f32_e32 v102, v48, v102
	v_sub_f32_e32 v103, v48, v103
	v_sub_f32_e32 v104, v48, v104
	v_sub_f32_e32 v105, v48, v105
	v_sub_f32_e32 v106, v48, v106
	v_sub_f32_e32 v107, v48, v107
	v_sub_f32_e32 v108, v48, v108
	v_sub_f32_e32 v109, v48, v109
	v_sub_f32_e32 v110, v48, v110
	v_sub_f32_e32 v111, v48, v111
	ds_read_b64_tr_b16 v[196:197], v250 offset:18432
	ds_read_b64_tr_b16 v[198:199], v250 offset:18944
	ds_read_b64_tr_b16 v[200:201], v250 offset:19456
	s_waitcnt lgkmcnt(14)
	v_mfma_f32_32x32x16_bf16 v[80:95], v[146:149], v[112:115], v[80:95]
	s_waitcnt lgkmcnt(13)
	v_mfma_f32_32x32x16_bf16 v[96:111], v[150:153], v[112:115], v[96:111]
	ds_read_b64_tr_b16 v[202:203], v250 offset:19968
	s_waitcnt lgkmcnt(13)
	v_mfma_f32_32x32x16_bf16 v[80:95], v[154:157], v[116:119], v[80:95]
	s_waitcnt lgkmcnt(12)
	v_mfma_f32_32x32x16_bf16 v[96:111], v[158:161], v[116:119], v[96:111]
	ds_read_b64_tr_b16 v[204:205], v250 offset:20480
	ds_read_b64_tr_b16 v[206:207], v250 offset:20992
	s_waitcnt lgkmcnt(13)
	v_mfma_f32_32x32x16_bf16 v[80:95], v[162:165], v[120:123], v[80:95]
	s_waitcnt lgkmcnt(12)
	v_mfma_f32_32x32x16_bf16 v[96:111], v[166:169], v[120:123], v[96:111]
	ds_read_b64_tr_b16 v[208:209], v250 offset:21504
	ds_read_b64_tr_b16 v[210:211], v250 offset:22016
	s_waitcnt lgkmcnt(13)
	v_mfma_f32_32x32x16_bf16 v[80:95], v[180:183], v[124:127], v[80:95]
	s_waitcnt lgkmcnt(12)
	v_mfma_f32_32x32x16_bf16 v[96:111], v[184:187], v[124:127], v[96:111]
	ds_read_b64_tr_b16 v[212:213], v250 offset:22528
	ds_read_b64_tr_b16 v[214:215], v250 offset:23040
	ds_read_b64_tr_b16 v[216:217], v250 offset:23552
	ds_read_b64_tr_b16 v[218:219], v250 offset:24064
	s_mov_b32 s46, s44
	s_mov_b32 s47, s44
	s_mov_b32 s45, s44
	s_cmp_le_i32 s60, s40
	s_cbranch_scc1 .LBB0_881
	v_cmp_gt_i32_e32 vcc, 0, v144
	v_cmp_gt_i32_e64 s[6:7], 1, v144
	s_and_b64 vcc, s[6:7], vcc
	s_nop 4
	v_cndmask_b32_e32 v80, v80, v235, vcc
	v_cmp_lt_i32_e32 vcc, 1, v144
	v_cmp_gt_i32_e64 s[36:37], 58, v144
	v_cmp_gt_i32_e64 s[38:39], 59, v144
	v_cndmask_b32_e32 v82, v235, v82, vcc
	v_cmp_lt_i32_e32 vcc, 2, v144
	v_cmp_gt_i32_e64 s[34:35], 57, v144
	s_and_b64 s[36:37], s[38:39], s[36:37]
	v_cndmask_b32_e32 v83, v235, v83, vcc
	v_cmp_lt_i32_e32 vcc, 7, v144
	v_cmp_gt_i32_e64 s[30:31], 56, v144
	s_and_b64 s[34:35], s[36:37], s[34:35]
	v_cndmask_b32_e32 v84, v235, v84, vcc
	v_cmp_lt_i32_e32 vcc, 8, v144
	v_cmp_gt_i32_e64 s[28:29], 51, v144
	s_and_b64 s[30:31], s[34:35], s[30:31]
	v_cndmask_b32_e32 v85, v235, v85, vcc
	v_cmp_lt_i32_e32 vcc, 9, v144
	v_cmp_gt_i32_e64 s[26:27], 50, v144
	s_and_b64 s[28:29], s[30:31], s[28:29]
	v_cndmask_b32_e32 v86, v235, v86, vcc
	v_cmp_lt_i32_e32 vcc, 10, v144
	v_cmp_gt_i32_e64 s[24:25], 49, v144
	s_and_b64 s[26:27], s[28:29], s[26:27]
	v_cndmask_b32_e32 v87, v235, v87, vcc
	v_cmp_lt_i32_e32 vcc, 15, v144
	v_cmp_gt_i32_e64 s[22:23], 48, v144
	s_and_b64 s[24:25], s[26:27], s[24:25]
	v_cndmask_b32_e32 v88, v235, v88, vcc
	v_cmp_lt_i32_e32 vcc, 16, v144
	v_cmp_gt_i32_e64 s[20:21], 43, v144
	s_and_b64 s[22:23], s[24:25], s[22:23]
	v_cndmask_b32_e32 v89, v235, v89, vcc
	v_cmp_lt_i32_e32 vcc, 17, v144
	v_cmp_gt_i32_e64 s[18:19], 42, v144
	s_and_b64 s[20:21], s[22:23], s[20:21]
	v_cndmask_b32_e32 v90, v235, v90, vcc
	v_cmp_lt_i32_e32 vcc, 18, v144
	v_cmp_gt_i32_e64 s[16:17], 41, v144
	s_and_b64 s[18:19], s[20:21], s[18:19]
	v_cndmask_b32_e32 v91, v235, v91, vcc
	v_cmp_lt_i32_e32 vcc, 23, v144
	v_cmp_gt_i32_e64 s[14:15], 40, v144
	s_and_b64 s[16:17], s[18:19], s[16:17]
	v_cndmask_b32_e32 v92, v235, v92, vcc
	v_cmp_lt_i32_e32 vcc, 24, v144
	v_cmp_gt_i32_e64 s[10:11], 35, v144
	s_and_b64 s[14:15], s[16:17], s[14:15]
	v_cndmask_b32_e32 v93, v235, v93, vcc
	v_cmp_lt_i32_e32 vcc, 25, v144
	v_cmp_gt_i32_e64 s[8:9], 34, v144
	s_and_b64 s[10:11], s[14:15], s[10:11]
	v_cndmask_b32_e64 v81, v81, v235, s[6:7]
	v_cndmask_b32_e32 v94, v235, v94, vcc
	v_cmp_lt_i32_e32 vcc, 26, v144
	v_cmp_gt_i32_e64 s[6:7], 33, v144
	s_and_b64 s[8:9], s[10:11], s[8:9]
	v_cndmask_b32_e32 v0, v235, v95, vcc
	v_cmp_gt_i32_e32 vcc, 32, v144
	s_and_b64 s[6:7], s[8:9], s[6:7]
	s_and_b64 vcc, s[6:7], vcc
	v_cndmask_b32_e64 v111, v111, v235, s[38:39]
	v_cndmask_b32_e64 v110, v110, v235, s[36:37]
	v_cndmask_b32_e64 v109, v109, v235, s[34:35]
	v_cndmask_b32_e64 v108, v108, v235, s[30:31]
	v_cndmask_b32_e64 v107, v107, v235, s[28:29]
	v_cndmask_b32_e64 v106, v106, v235, s[26:27]
	v_cndmask_b32_e64 v105, v105, v235, s[24:25]
	v_cndmask_b32_e64 v104, v104, v235, s[22:23]
	v_cndmask_b32_e64 v103, v103, v235, s[20:21]
	v_cndmask_b32_e64 v102, v102, v235, s[18:19]
	v_cndmask_b32_e64 v101, v101, v235, s[16:17]
	v_cndmask_b32_e64 v100, v100, v235, s[14:15]
	v_cndmask_b32_e64 v99, v99, v235, s[10:11]
	v_cndmask_b32_e64 v98, v98, v235, s[8:9]
	v_cndmask_b32_e64 v97, v97, v235, s[6:7]
	v_cndmask_b32_e32 v95, v95, v0, vcc
	v_cndmask_b32_e32 v96, v96, v235, vcc
